# v26: v23 + no L1 invalidate at the grid barrier (before it a CU only loads kernel inputs and only stores whole lines of the bf16 copies, so nothing it loads afterwards can be stale in its L1)
# speedup vs baseline: 1.0027x; 1.0027x over previous
.LBB0_171:
	s_or_b64 exec, exec, s[12:13]
	s_waitcnt vmcnt(0)
	s_waitcnt vmcnt(0)

.LBB0_189:
	s_or_b64 exec, exec, s[8:9]
	s_mov_b64 s[8:9], exec
	v_mbcnt_lo_u32_b32 v2, s8, 0
	v_mbcnt_hi_u32_b32 v2, s9, v2
	v_cmp_eq_u32_e32 vcc, 0, v2
	s_waitcnt vmcnt(0)
	s_and_saveexec_b64 s[12:13], vcc
	s_cbranch_execz .LBB0_191
	s_bcnt1_i32_b64 s8, s[8:9]
	v_mov_b32_e32 v2, 0x2000
	v_mov_b32_e32 v3, s8
	global_atomic_add v2, v3, s[6:7] offset:1024
